# v10 + accumulators zeroed with v_mov_b64 pairs before each K-loop
# baseline (speedup 1.0000x reference)
.LBB0_108:
	s_ashr_i32 s15, s14, 31
	s_lshl_b64 s[16:17], s[14:15], 21
	v_readlane_b32 s18, v251, 17
	v_readlane_b32 s19, v251, 18
	s_add_u32 s16, s18, s16
	s_addc_u32 s17, s19, s17
	s_and_b64 s[18:19], s[2:3], exec
	s_cselect_b32 s15, s17, s21
	s_cselect_b32 s42, s16, s20
	s_ashr_i32 s13, s12, 31
	s_lshl_b64 s[18:19], s[12:13], 21
	s_add_u32 s18, s76, s18
	s_addc_u32 s19, s77, s19
	s_and_b64 s[24:25], s[2:3], exec
	s_cselect_b32 s13, s19, s23
	s_cselect_b32 s43, s18, s22
	s_add_u32 s20, s20, 0x104000
	s_addc_u32 s21, s21, 0
	s_add_u32 s44, s22, 0x8000
	v_mov_b32_e32 v66, 0
	s_addc_u32 s45, s23, 0
	s_mov_b32 s46, -2
	v_mov_b64_e32 v[2:3], 0
	v_mov_b64_e32 v[4:5], 0
	v_mov_b64_e32 v[6:7], 0
	v_mov_b64_e32 v[8:9], 0
	v_mov_b64_e32 v[10:11], 0
	v_mov_b64_e32 v[12:13], 0
	v_mov_b64_e32 v[14:15], 0
	v_mov_b64_e32 v[16:17], 0
	v_mov_b64_e32 v[18:19], 0
	v_mov_b64_e32 v[20:21], 0
	v_mov_b64_e32 v[22:23], 0
	v_mov_b64_e32 v[24:25], 0
	v_mov_b64_e32 v[26:27], 0
	v_mov_b64_e32 v[28:29], 0
	v_mov_b64_e32 v[30:31], 0
	v_mov_b64_e32 v[32:33], 0
	v_mov_b64_e32 v[34:35], 0
	v_mov_b64_e32 v[36:37], 0
	v_mov_b64_e32 v[38:39], 0
	v_mov_b64_e32 v[40:41], 0
	v_mov_b64_e32 v[42:43], 0
	v_mov_b64_e32 v[44:45], 0
	v_mov_b64_e32 v[46:47], 0
	v_mov_b64_e32 v[48:49], 0
	v_mov_b64_e32 v[50:51], 0
	v_mov_b64_e32 v[52:53], 0
	v_mov_b64_e32 v[54:55], 0
	v_mov_b64_e32 v[56:57], 0
	v_mov_b64_e32 v[58:59], 0
	v_mov_b64_e32 v[60:61], 0
	v_mov_b64_e32 v[62:63], 0
	v_mov_b64_e32 v[64:65], 0
	v_mov_b64_e32 v[66:67], 0
	v_mov_b64_e32 v[68:69], 0
	v_mov_b64_e32 v[70:71], 0
	v_mov_b64_e32 v[72:73], 0
	v_mov_b64_e32 v[74:75], 0
	v_mov_b64_e32 v[76:77], 0
	v_mov_b64_e32 v[78:79], 0
	v_mov_b64_e32 v[80:81], 0
	v_mov_b64_e32 v[82:83], 0
	v_mov_b64_e32 v[84:85], 0
	v_mov_b64_e32 v[86:87], 0
	v_mov_b64_e32 v[88:89], 0
	v_mov_b64_e32 v[90:91], 0
	v_mov_b64_e32 v[92:93], 0
	v_mov_b64_e32 v[94:95], 0
	v_mov_b64_e32 v[96:97], 0
	v_mov_b64_e32 v[98:99], 0
	v_mov_b64_e32 v[100:101], 0
	v_mov_b64_e32 v[102:103], 0
	v_mov_b64_e32 v[104:105], 0
	v_mov_b64_e32 v[106:107], 0
	v_mov_b64_e32 v[108:109], 0
	v_mov_b64_e32 v[110:111], 0
	v_mov_b64_e32 v[112:113], 0
	v_mov_b64_e32 v[114:115], 0
	v_mov_b64_e32 v[116:117], 0
	v_mov_b64_e32 v[118:119], 0
	v_mov_b64_e32 v[120:121], 0
	v_mov_b64_e32 v[122:123], 0
	v_mov_b64_e32 v[124:125], 0
	v_mov_b64_e32 v[126:127], 0
	v_mov_b64_e32 v[128:129], 0

.LBB0_375:
	s_ashr_i32 s21, s20, 31
	s_lshl_b64 s[22:23], s[20:21], 21
	v_readlane_b32 s24, v251, 17
	v_readlane_b32 s25, v251, 18
	s_add_u32 s22, s24, s22
	s_addc_u32 s23, s25, s23
	s_and_b64 s[24:25], s[2:3], exec
	s_cselect_b32 s21, s23, s27
	s_cselect_b32 s80, s22, s26
	s_ashr_i32 s19, s18, 31
	s_lshl_b64 s[24:25], s[18:19], 21
	s_add_u32 s24, s42, s24
	s_addc_u32 s25, s43, s25
	s_and_b64 s[36:37], s[2:3], exec
	s_cselect_b32 s19, s25, s35
	s_cselect_b32 s81, s24, s34
	s_add_u32 s26, s26, 0x104000
	s_addc_u32 s27, s27, 0
	s_add_u32 s83, s34, 0x8000
	v_mov_b32_e32 v66, 0
	s_addc_u32 s86, s35, 0
	s_mov_b32 s87, -2
	v_mov_b64_e32 v[2:3], 0
	v_mov_b64_e32 v[4:5], 0
	v_mov_b64_e32 v[6:7], 0
	v_mov_b64_e32 v[8:9], 0
	v_mov_b64_e32 v[10:11], 0
	v_mov_b64_e32 v[12:13], 0
	v_mov_b64_e32 v[14:15], 0
	v_mov_b64_e32 v[16:17], 0
	v_mov_b64_e32 v[18:19], 0
	v_mov_b64_e32 v[20:21], 0
	v_mov_b64_e32 v[22:23], 0
	v_mov_b64_e32 v[24:25], 0
	v_mov_b64_e32 v[26:27], 0
	v_mov_b64_e32 v[28:29], 0
	v_mov_b64_e32 v[30:31], 0
	v_mov_b64_e32 v[32:33], 0
	v_mov_b64_e32 v[34:35], 0
	v_mov_b64_e32 v[36:37], 0
	v_mov_b64_e32 v[38:39], 0
	v_mov_b64_e32 v[40:41], 0
	v_mov_b64_e32 v[42:43], 0
	v_mov_b64_e32 v[44:45], 0
	v_mov_b64_e32 v[46:47], 0
	v_mov_b64_e32 v[48:49], 0
	v_mov_b64_e32 v[50:51], 0
	v_mov_b64_e32 v[52:53], 0
	v_mov_b64_e32 v[54:55], 0
	v_mov_b64_e32 v[56:57], 0
	v_mov_b64_e32 v[58:59], 0
	v_mov_b64_e32 v[60:61], 0
	v_mov_b64_e32 v[62:63], 0
	v_mov_b64_e32 v[64:65], 0
	v_mov_b64_e32 v[66:67], 0
	v_mov_b64_e32 v[68:69], 0
	v_mov_b64_e32 v[70:71], 0
	v_mov_b64_e32 v[72:73], 0
	v_mov_b64_e32 v[74:75], 0
	v_mov_b64_e32 v[76:77], 0
	v_mov_b64_e32 v[78:79], 0
	v_mov_b64_e32 v[80:81], 0
	v_mov_b64_e32 v[82:83], 0
	v_mov_b64_e32 v[84:85], 0
	v_mov_b64_e32 v[86:87], 0
	v_mov_b64_e32 v[88:89], 0
	v_mov_b64_e32 v[90:91], 0
	v_mov_b64_e32 v[92:93], 0
	v_mov_b64_e32 v[94:95], 0
	v_mov_b64_e32 v[96:97], 0
	v_mov_b64_e32 v[98:99], 0
	v_mov_b64_e32 v[100:101], 0
	v_mov_b64_e32 v[102:103], 0
	v_mov_b64_e32 v[104:105], 0
	v_mov_b64_e32 v[106:107], 0
	v_mov_b64_e32 v[108:109], 0
	v_mov_b64_e32 v[110:111], 0
	v_mov_b64_e32 v[112:113], 0
	v_mov_b64_e32 v[114:115], 0
	v_mov_b64_e32 v[116:117], 0
	v_mov_b64_e32 v[118:119], 0
	v_mov_b64_e32 v[120:121], 0
	v_mov_b64_e32 v[122:123], 0
	v_mov_b64_e32 v[124:125], 0
	v_mov_b64_e32 v[126:127], 0
	v_mov_b64_e32 v[128:129], 0

.LBB0_535:
	s_ashr_i32 s21, s20, 31
	s_lshl_b64 s[22:23], s[20:21], 21
	v_readlane_b32 s24, v251, 17
	v_readlane_b32 s25, v251, 18
	s_add_u32 s22, s24, s22
	s_addc_u32 s23, s25, s23
	s_and_b64 s[24:25], s[2:3], exec
	s_cselect_b32 s21, s23, s27
	s_cselect_b32 s74, s22, s26
	s_ashr_i32 s19, s18, 31
	s_lshl_b64 s[24:25], s[18:19], 21
	s_add_u32 s24, s39, s24
	s_addc_u32 s25, s40, s25
	s_and_b64 s[34:35], s[2:3], exec
	s_cselect_b32 s19, s25, s31
	s_cselect_b32 s75, s24, s30
	s_add_u32 s26, s26, 0x104000
	s_addc_u32 s27, s27, 0
	s_add_u32 s78, s30, 0x8000
	v_mov_b32_e32 v66, 0
	s_addc_u32 s79, s31, 0
	s_mov_b32 s80, -2
	v_mov_b64_e32 v[2:3], 0
	v_mov_b64_e32 v[4:5], 0
	v_mov_b64_e32 v[6:7], 0
	v_mov_b64_e32 v[8:9], 0
	v_mov_b64_e32 v[10:11], 0
	v_mov_b64_e32 v[12:13], 0
	v_mov_b64_e32 v[14:15], 0
	v_mov_b64_e32 v[16:17], 0
	v_mov_b64_e32 v[18:19], 0
	v_mov_b64_e32 v[20:21], 0
	v_mov_b64_e32 v[22:23], 0
	v_mov_b64_e32 v[24:25], 0
	v_mov_b64_e32 v[26:27], 0
	v_mov_b64_e32 v[28:29], 0
	v_mov_b64_e32 v[30:31], 0
	v_mov_b64_e32 v[32:33], 0
	v_mov_b64_e32 v[34:35], 0
	v_mov_b64_e32 v[36:37], 0
	v_mov_b64_e32 v[38:39], 0
	v_mov_b64_e32 v[40:41], 0
	v_mov_b64_e32 v[42:43], 0
	v_mov_b64_e32 v[44:45], 0
	v_mov_b64_e32 v[46:47], 0
	v_mov_b64_e32 v[48:49], 0
	v_mov_b64_e32 v[50:51], 0
	v_mov_b64_e32 v[52:53], 0
	v_mov_b64_e32 v[54:55], 0
	v_mov_b64_e32 v[56:57], 0
	v_mov_b64_e32 v[58:59], 0
	v_mov_b64_e32 v[60:61], 0
	v_mov_b64_e32 v[62:63], 0
	v_mov_b64_e32 v[64:65], 0
	v_mov_b64_e32 v[66:67], 0
	v_mov_b64_e32 v[68:69], 0
	v_mov_b64_e32 v[70:71], 0
	v_mov_b64_e32 v[72:73], 0
	v_mov_b64_e32 v[74:75], 0
	v_mov_b64_e32 v[76:77], 0
	v_mov_b64_e32 v[78:79], 0
	v_mov_b64_e32 v[80:81], 0
	v_mov_b64_e32 v[82:83], 0
	v_mov_b64_e32 v[84:85], 0
	v_mov_b64_e32 v[86:87], 0
	v_mov_b64_e32 v[88:89], 0
	v_mov_b64_e32 v[90:91], 0
	v_mov_b64_e32 v[92:93], 0
	v_mov_b64_e32 v[94:95], 0
	v_mov_b64_e32 v[96:97], 0
	v_mov_b64_e32 v[98:99], 0
	v_mov_b64_e32 v[100:101], 0
	v_mov_b64_e32 v[102:103], 0
	v_mov_b64_e32 v[104:105], 0
	v_mov_b64_e32 v[106:107], 0
	v_mov_b64_e32 v[108:109], 0
	v_mov_b64_e32 v[110:111], 0
	v_mov_b64_e32 v[112:113], 0
	v_mov_b64_e32 v[114:115], 0
	v_mov_b64_e32 v[116:117], 0
	v_mov_b64_e32 v[118:119], 0
	v_mov_b64_e32 v[120:121], 0
	v_mov_b64_e32 v[122:123], 0
	v_mov_b64_e32 v[124:125], 0
	v_mov_b64_e32 v[126:127], 0
	v_mov_b64_e32 v[128:129], 0

.LBB0_1087:
	s_ashr_i32 s25, s24, 31
	s_lshl_b64 s[26:27], s[24:25], 21
	s_add_u32 s26, s28, s26
	s_addc_u32 s27, s29, s27
	s_and_b64 s[30:31], s[6:7], exec
	s_cselect_b32 s25, s27, s37
	s_cselect_b32 s35, s26, s36
	s_ashr_i32 s23, s22, 31
	s_lshl_b64 s[30:31], s[22:23], 21
	s_add_u32 s30, s52, s30
	s_addc_u32 s31, s53, s31
	s_and_b64 s[40:41], s[6:7], exec
	s_cselect_b32 s23, s31, s39
	s_cselect_b32 s69, s30, s38
	s_add_u32 s36, s36, 0x104000
	s_addc_u32 s37, s37, 0
	s_add_u32 s70, s38, 0x8000
	v_mov_b32_e32 v2, 0
	s_addc_u32 s71, s39, 0
	s_mov_b32 s72, -2
	s_waitcnt lgkmcnt(0)
	v_mov_b64_e32 v[2:3], 0
	v_mov_b64_e32 v[4:5], 0
	v_mov_b64_e32 v[6:7], 0
	v_mov_b64_e32 v[8:9], 0
	v_mov_b64_e32 v[10:11], 0
	v_mov_b64_e32 v[12:13], 0
	v_mov_b64_e32 v[14:15], 0
	v_mov_b64_e32 v[16:17], 0
	v_mov_b64_e32 v[18:19], 0
	v_mov_b64_e32 v[20:21], 0
	v_mov_b64_e32 v[22:23], 0
	v_mov_b64_e32 v[24:25], 0
	v_mov_b64_e32 v[26:27], 0
	v_mov_b64_e32 v[28:29], 0
	v_mov_b64_e32 v[30:31], 0
	v_mov_b64_e32 v[32:33], 0
	v_mov_b64_e32 v[34:35], 0
	v_mov_b64_e32 v[36:37], 0
	v_mov_b64_e32 v[38:39], 0
	v_mov_b64_e32 v[40:41], 0
	v_mov_b64_e32 v[42:43], 0
	v_mov_b64_e32 v[44:45], 0
	v_mov_b64_e32 v[46:47], 0
	v_mov_b64_e32 v[48:49], 0
	v_mov_b64_e32 v[50:51], 0
	v_mov_b64_e32 v[52:53], 0
	v_mov_b64_e32 v[54:55], 0
	v_mov_b64_e32 v[56:57], 0
	v_mov_b64_e32 v[58:59], 0
	v_mov_b64_e32 v[60:61], 0
	v_mov_b64_e32 v[62:63], 0
	v_mov_b64_e32 v[64:65], 0
	v_mov_b64_e32 v[66:67], 0
	v_mov_b64_e32 v[68:69], 0
	v_mov_b64_e32 v[70:71], 0
	v_mov_b64_e32 v[72:73], 0
	v_mov_b64_e32 v[74:75], 0
	v_mov_b64_e32 v[76:77], 0
	v_mov_b64_e32 v[78:79], 0
	v_mov_b64_e32 v[80:81], 0
	v_mov_b64_e32 v[82:83], 0
	v_mov_b64_e32 v[84:85], 0
	v_mov_b64_e32 v[86:87], 0
	v_mov_b64_e32 v[88:89], 0
	v_mov_b64_e32 v[90:91], 0
	v_mov_b64_e32 v[92:93], 0
	v_mov_b64_e32 v[94:95], 0
	v_mov_b64_e32 v[96:97], 0
	v_mov_b64_e32 v[98:99], 0
	v_mov_b64_e32 v[100:101], 0
	v_mov_b64_e32 v[102:103], 0
	v_mov_b64_e32 v[104:105], 0
	v_mov_b64_e32 v[106:107], 0
	v_mov_b64_e32 v[108:109], 0
	v_mov_b64_e32 v[110:111], 0
	v_mov_b64_e32 v[112:113], 0
	v_mov_b64_e32 v[114:115], 0
	v_mov_b64_e32 v[116:117], 0
	v_mov_b64_e32 v[118:119], 0
	v_mov_b64_e32 v[120:121], 0
	v_mov_b64_e32 v[122:123], 0
	v_mov_b64_e32 v[124:125], 0
	v_mov_b64_e32 v[126:127], 0
	v_mov_b64_e32 v[128:129], 0

.LBB0_1214:
	s_ashr_i32 s21, s20, 31
	s_lshl_b64 s[22:23], s[20:21], 21
	s_add_u32 s22, s10, s22
	s_addc_u32 s23, s11, s23
	s_and_b64 s[24:25], s[4:5], exec
	s_cselect_b32 s21, s23, s29
	s_cselect_b32 s56, s22, s28
	s_ashr_i32 s19, s18, 31
	s_lshl_b64 s[24:25], s[18:19], 21
	s_add_u32 s24, s65, s24
	v_readlane_b32 s19, v251, 50
	s_addc_u32 s25, s19, s25
	s_and_b64 s[34:35], s[4:5], exec
	s_cselect_b32 s19, s25, s31
	s_cselect_b32 s57, s24, s30
	s_add_u32 s28, s28, 0x104000
	s_addc_u32 s29, s29, 0
	s_add_u32 s59, s30, 0x8000
	v_mov_b32_e32 v2, 0
	s_addc_u32 s60, s31, 0
	s_mov_b32 s61, -2
	v_mov_b64_e32 v[2:3], 0
	v_mov_b64_e32 v[4:5], 0
	v_mov_b64_e32 v[6:7], 0
	v_mov_b64_e32 v[8:9], 0
	v_mov_b64_e32 v[10:11], 0
	v_mov_b64_e32 v[12:13], 0
	v_mov_b64_e32 v[14:15], 0
	v_mov_b64_e32 v[16:17], 0
	v_mov_b64_e32 v[18:19], 0
	v_mov_b64_e32 v[20:21], 0
	v_mov_b64_e32 v[22:23], 0
	v_mov_b64_e32 v[24:25], 0
	v_mov_b64_e32 v[26:27], 0
	v_mov_b64_e32 v[28:29], 0
	v_mov_b64_e32 v[30:31], 0
	v_mov_b64_e32 v[32:33], 0
	v_mov_b64_e32 v[34:35], 0
	v_mov_b64_e32 v[36:37], 0
	v_mov_b64_e32 v[38:39], 0
	v_mov_b64_e32 v[40:41], 0
	v_mov_b64_e32 v[42:43], 0
	v_mov_b64_e32 v[44:45], 0
	v_mov_b64_e32 v[46:47], 0
	v_mov_b64_e32 v[48:49], 0
	v_mov_b64_e32 v[50:51], 0
	v_mov_b64_e32 v[52:53], 0
	v_mov_b64_e32 v[54:55], 0
	v_mov_b64_e32 v[56:57], 0
	v_mov_b64_e32 v[58:59], 0
	v_mov_b64_e32 v[60:61], 0
	v_mov_b64_e32 v[62:63], 0
	v_mov_b64_e32 v[64:65], 0
	v_mov_b64_e32 v[66:67], 0
	v_mov_b64_e32 v[68:69], 0
	v_mov_b64_e32 v[70:71], 0
	v_mov_b64_e32 v[72:73], 0
	v_mov_b64_e32 v[74:75], 0
	v_mov_b64_e32 v[76:77], 0
	v_mov_b64_e32 v[78:79], 0
	v_mov_b64_e32 v[80:81], 0
	v_mov_b64_e32 v[82:83], 0
	v_mov_b64_e32 v[84:85], 0
	v_mov_b64_e32 v[86:87], 0
	v_mov_b64_e32 v[88:89], 0
	v_mov_b64_e32 v[90:91], 0
	v_mov_b64_e32 v[92:93], 0
	v_mov_b64_e32 v[94:95], 0
	v_mov_b64_e32 v[96:97], 0
	v_mov_b64_e32 v[98:99], 0
	v_mov_b64_e32 v[100:101], 0
	v_mov_b64_e32 v[102:103], 0
	v_mov_b64_e32 v[104:105], 0
	v_mov_b64_e32 v[106:107], 0
	v_mov_b64_e32 v[108:109], 0
	v_mov_b64_e32 v[110:111], 0
	v_mov_b64_e32 v[112:113], 0
	v_mov_b64_e32 v[114:115], 0
	v_mov_b64_e32 v[116:117], 0
	v_mov_b64_e32 v[118:119], 0
	v_mov_b64_e32 v[120:121], 0
	v_mov_b64_e32 v[122:123], 0
	v_mov_b64_e32 v[124:125], 0
	v_mov_b64_e32 v[126:127], 0
	v_mov_b64_e32 v[128:129], 0

.LBB0_1291:
	s_ashr_i32 s29, s28, 31
	s_lshl_b64 s[30:31], s[28:29], 23
	s_add_u32 s30, s84, s30
	s_addc_u32 s31, s85, s31
	s_and_b64 s[34:35], s[6:7], exec
	s_cselect_b32 s14, s31, s41
	s_cselect_b32 s29, s30, s40
	s_ashr_i32 s27, s26, 31
	s_lshl_b64 s[34:35], s[26:27], 23
	s_add_u32 s34, s51, s34
	v_readlane_b32 s27, v251, 62
	s_addc_u32 s35, s27, s35
	s_and_b64 s[44:45], s[6:7], exec
	s_cselect_b32 s27, s35, s43
	s_cselect_b32 s37, s34, s42
	s_add_u32 s40, s40, 0x404000
	s_addc_u32 s41, s41, 0
	s_add_u32 s39, s42, 0x8000
	v_mov_b32_e32 v2, 0
	s_addc_u32 s65, s43, 0
	s_mov_b32 s66, -2
	s_waitcnt lgkmcnt(0)
	v_mov_b64_e32 v[2:3], 0
	v_mov_b64_e32 v[4:5], 0
	v_mov_b64_e32 v[6:7], 0
	v_mov_b64_e32 v[8:9], 0
	v_mov_b64_e32 v[10:11], 0
	v_mov_b64_e32 v[12:13], 0
	v_mov_b64_e32 v[14:15], 0
	v_mov_b64_e32 v[16:17], 0
	v_mov_b64_e32 v[18:19], 0
	v_mov_b64_e32 v[20:21], 0
	v_mov_b64_e32 v[22:23], 0
	v_mov_b64_e32 v[24:25], 0
	v_mov_b64_e32 v[26:27], 0
	v_mov_b64_e32 v[28:29], 0
	v_mov_b64_e32 v[30:31], 0
	v_mov_b64_e32 v[32:33], 0
	v_mov_b64_e32 v[34:35], 0
	v_mov_b64_e32 v[36:37], 0
	v_mov_b64_e32 v[38:39], 0
	v_mov_b64_e32 v[40:41], 0
	v_mov_b64_e32 v[42:43], 0
	v_mov_b64_e32 v[44:45], 0
	v_mov_b64_e32 v[46:47], 0
	v_mov_b64_e32 v[48:49], 0
	v_mov_b64_e32 v[50:51], 0
	v_mov_b64_e32 v[52:53], 0
	v_mov_b64_e32 v[54:55], 0
	v_mov_b64_e32 v[56:57], 0
	v_mov_b64_e32 v[58:59], 0
	v_mov_b64_e32 v[60:61], 0
	v_mov_b64_e32 v[62:63], 0
	v_mov_b64_e32 v[64:65], 0
	v_mov_b64_e32 v[66:67], 0
	v_mov_b64_e32 v[68:69], 0
	v_mov_b64_e32 v[70:71], 0
	v_mov_b64_e32 v[72:73], 0
	v_mov_b64_e32 v[74:75], 0
	v_mov_b64_e32 v[76:77], 0
	v_mov_b64_e32 v[78:79], 0
	v_mov_b64_e32 v[80:81], 0
	v_mov_b64_e32 v[82:83], 0
	v_mov_b64_e32 v[84:85], 0
	v_mov_b64_e32 v[86:87], 0
	v_mov_b64_e32 v[88:89], 0
	v_mov_b64_e32 v[90:91], 0
	v_mov_b64_e32 v[92:93], 0
	v_mov_b64_e32 v[94:95], 0
	v_mov_b64_e32 v[96:97], 0
	v_mov_b64_e32 v[98:99], 0
	v_mov_b64_e32 v[100:101], 0
	v_mov_b64_e32 v[102:103], 0
	v_mov_b64_e32 v[104:105], 0
	v_mov_b64_e32 v[106:107], 0
	v_mov_b64_e32 v[108:109], 0
	v_mov_b64_e32 v[110:111], 0
	v_mov_b64_e32 v[112:113], 0
	v_mov_b64_e32 v[114:115], 0
	v_mov_b64_e32 v[116:117], 0
	v_mov_b64_e32 v[118:119], 0
	v_mov_b64_e32 v[120:121], 0
	v_mov_b64_e32 v[122:123], 0
	v_mov_b64_e32 v[124:125], 0
	v_mov_b64_e32 v[126:127], 0
	v_mov_b64_e32 v[128:129], 0

.LBB0_1386:
	s_ashr_i32 s21, s20, 31
	s_lshl_b64 s[22:23], s[20:21], 21
	s_add_u32 s22, s0, s22
	s_addc_u32 s23, s1, s23
	s_and_b64 s[24:25], s[2:3], exec
	s_cselect_b32 s21, s23, s31
	s_cselect_b32 s27, s22, s30
	s_ashr_i32 s19, s18, 31
	s_lshl_b64 s[24:25], s[18:19], 21
	s_add_u32 s24, s48, s24
	s_addc_u32 s25, s49, s25
	s_and_b64 s[36:37], s[2:3], exec
	s_cselect_b32 s19, s25, s35
	s_cselect_b32 s29, s24, s34
	s_add_u32 s30, s30, 0x104000
	s_addc_u32 s31, s31, 0
	s_add_u32 s52, s34, 0x8000
	v_mov_b32_e32 v2, 0
	s_addc_u32 s53, s35, 0
	s_mov_b32 s54, -2
	v_mov_b64_e32 v[2:3], 0
	v_mov_b64_e32 v[4:5], 0
	v_mov_b64_e32 v[6:7], 0
	v_mov_b64_e32 v[8:9], 0
	v_mov_b64_e32 v[10:11], 0
	v_mov_b64_e32 v[12:13], 0
	v_mov_b64_e32 v[14:15], 0
	v_mov_b64_e32 v[16:17], 0
	v_mov_b64_e32 v[18:19], 0
	v_mov_b64_e32 v[20:21], 0
	v_mov_b64_e32 v[22:23], 0
	v_mov_b64_e32 v[24:25], 0
	v_mov_b64_e32 v[26:27], 0
	v_mov_b64_e32 v[28:29], 0
	v_mov_b64_e32 v[30:31], 0
	v_mov_b64_e32 v[32:33], 0
	v_mov_b64_e32 v[34:35], 0
	v_mov_b64_e32 v[36:37], 0
	v_mov_b64_e32 v[38:39], 0
	v_mov_b64_e32 v[40:41], 0
	v_mov_b64_e32 v[42:43], 0
	v_mov_b64_e32 v[44:45], 0
	v_mov_b64_e32 v[46:47], 0
	v_mov_b64_e32 v[48:49], 0
	v_mov_b64_e32 v[50:51], 0
	v_mov_b64_e32 v[52:53], 0
	v_mov_b64_e32 v[54:55], 0
	v_mov_b64_e32 v[56:57], 0
	v_mov_b64_e32 v[58:59], 0
	v_mov_b64_e32 v[60:61], 0
	v_mov_b64_e32 v[70:71], 0
	v_mov_b64_e32 v[72:73], 0
	v_mov_b64_e32 v[82:83], 0
	v_mov_b64_e32 v[84:85], 0
	v_mov_b64_e32 v[86:87], 0
	v_mov_b64_e32 v[88:89], 0
	v_mov_b64_e32 v[90:91], 0
	v_mov_b64_e32 v[92:93], 0
	v_mov_b64_e32 v[94:95], 0
	v_mov_b64_e32 v[96:97], 0
	v_mov_b64_e32 v[98:99], 0
	v_mov_b64_e32 v[100:101], 0
	v_mov_b64_e32 v[102:103], 0
	v_mov_b64_e32 v[104:105], 0
	v_mov_b64_e32 v[106:107], 0
	v_mov_b64_e32 v[108:109], 0
	v_mov_b64_e32 v[110:111], 0
	v_mov_b64_e32 v[112:113], 0
	v_mov_b64_e32 v[114:115], 0
	v_mov_b64_e32 v[116:117], 0
	v_mov_b64_e32 v[118:119], 0
	v_mov_b64_e32 v[120:121], 0
	v_mov_b64_e32 v[122:123], 0
	v_mov_b64_e32 v[124:125], 0
	v_mov_b64_e32 v[126:127], 0
	v_mov_b64_e32 v[128:129], 0
	v_mov_b64_e32 v[130:131], 0
	v_mov_b64_e32 v[132:133], 0
	v_mov_b64_e32 v[134:135], 0
	v_mov_b64_e32 v[136:137], 0
	v_mov_b64_e32 v[138:139], 0
	v_mov_b64_e32 v[140:141], 0
	v_mov_b64_e32 v[142:143], 0
	v_mov_b64_e32 v[144:145], 0
